# P12 SwiGLU epilogue rewritten: per-row sum of squares as one float (f32 atomics from the P10 epilogue), loaded with shift vector at tile header, no memory wait before epilogue math; P10 pipelined epil
# speedup vs baseline: 1.0389x; 1.0389x over previous
; #define SEAM(k) do { if (IN(k) && IN((k) + 1)) { if (a.ph_hi > 4096) cg::this_grid().sync(); else xcd_barrier(xbar); } } while (0)
; __global__ void __launch_bounds__(512, 2) fwd_kernel(Args a) {
;     ...
;     if (IN(1)) { norm_mod_phase(a.in[I_X], a.in[I_CTX], MALL, a.in[I_N1G], mod, 0, 1, XN, gw, NGW, lane);
;         shiftw_phase((const bf16_t*)(ws + WS_WIN), ZW, mod, 3, (float*)(ws + WS_SHW1), gw, NGW, lane, true); shiftw_phase((const bf16_t*)(ws + WS_W2A), NFF2, mod, 6, (float*)(ws + WS_SHW2), NGW - 1 - gw, NGW, lane, false); } SEAM(1);
.LBB0_120:
	v_lshl_add_u32 v252, s92, 6, v146
	v_lshlrev_b32_e32 v252, 2, v252
	v_mov_b32_e32 v253, 0
	s_add_u32 s98, s88, 0x3ce00000
	s_addc_u32 s99, s89, 0
	v_cmp_gt_u32_e32 vcc, 0x40000, v252
	s_nop 4
	s_and_saveexec_b64 s[100:101], vcc
	global_store_dword v252, v253, s[98:99]
	s_or_b64 exec, exec, s[100:101]
	s_cmp_gt_i32 s91, 1
	s_cselect_b64 s[0:1], -1, 0
	s_and_b64 s[4:5], s[6:7], s[0:1]
	s_andn2_b64 vcc, exec, s[4:5]
	s_cbranch_vccnz .LBB0_184
	s_cmpk_lt_u32 s91, 0x1001
	s_mov_b64 s[4:5], -1
	s_cbranch_scc0 .LBB0_171
	s_waitcnt vmcnt(0)
	s_waitcnt lgkmcnt(0)
	s_barrier
	s_mov_b64 s[4:5], exec
	v_readlane_b32 s6, v242, 3
	v_readlane_b32 s7, v242, 4
	s_and_b64 s[6:7], s[4:5], s[6:7]
	s_mov_b64 exec, s[6:7]
	s_cbranch_execz .LBB0_170
	s_add_i32 s6, 0, 0x23fc0
	v_mov_b32_e32 v2, s6
	s_waitcnt vmcnt(0) expcnt(0) lgkmcnt(0)
	ds_read_b32 v4, v2
	s_add_i32 s6, 0, 0x23fc4
	v_mov_b32_e32 v2, s6
	ds_read_b32 v2, v2
	s_waitcnt lgkmcnt(1)
	v_cmp_ne_u32_e32 vcc, 0, v4
	s_cbranch_vccnz .LBB0_138
	v_readlane_b32 s6, v242, 0
	v_readlane_b32 s7, v242, 1
	s_load_dwordx2 s[12:13], s[6:7], 0x4
	s_add_u32 s6, s88, 0x1000
	s_addc_u32 s7, s89, 0
	s_add_u32 s8, s88, 0x1100
	s_addc_u32 s9, s89, 0
	s_waitcnt lgkmcnt(0)
	s_mul_i32 s33, s12, s50
	s_add_u32 s12, s88, 0x1200
	s_mul_i32 s33, s33, s13
	s_addc_u32 s13, s89, 0
	s_add_u32 s24, s88, 0x1300
	s_addc_u32 s25, s89, 0
	s_mov_b32 s34, 1
	v_mov_b32_e32 v18, 0
	s_branch .LBB0_126

; DEV u32x4 pack8v(const f32x4 a, const f32x4 b) { u32x4 w; w.x = cvt_pk_bf16(a[0], a[1]); w.y = cvt_pk_bf16(a[2], a[3]); w.z = cvt_pk_bf16(b[0], b[1]); w.w = cvt_pk_bf16(b[2], b[3]); return w; }
;     DEV void operator()(const f32x4 (&acc)[2][2][4][2], const Unit& u, int wr, int wc, int fr, int fq) const {
;     ...
;             f32x4 gv[2], gs[2];
; #pragma unroll
;             for (int n = 0; n < 2; ++n) { gv[n] = *(const f32x4*)(mod + (size_t)b * NMOD + gate_i * D + col0 + bj * 128 + NS * n) * coef;
;                 if (has_xn) gs[n] = *(const f32x4*)(g + col0 + bj * 128 + 4 * n) * (*(const f32x4*)(mod + (size_t)b * NMOD + scale_i * D + col0 + bj * 128 + 4 * n) + 1.f); }
; #pragma unroll
;             for (int ai = 0; ai < 2; ++ai)
; #pragma unroll
;                 for (int m = 0; m < 4; ++m) {
;                     const size_t p = (size_t)(row0 + ai * 128 + m * 16) * D + col0 + bj * 128;
;                     const f32x4 r0 = *(const f32x4*)(res + p), r1 = *(const f32x4*)(res + p + NS);
;                     const f32x4 o0 = r0 + gv[0] * acc[ai][bj][m][0], o1 = r1 + gv[1] * acc[ai][bj][m][1];
;                     *(f32x4*)(out + p) = o0; *(f32x4*)(out + p + NS) = o1;
;                     if (has_xn) { ss[ai * 4 + m] += (o0[0] * o0[0] + o0[1] * o0[1]) + (o0[2] * o0[2] + o0[3] * o0[3]) + (o1[0] * o1[0] + o1[1] * o1[1]) + (o1[2] * o1[2] + o1[3] * o1[3]);
;                         *(u32x4*)(xn + (size_t)(grow0 + ai * 128 + m * 16) * D + col0 + bj * 128) = pack8v(o0 * gs[0], o1 * gs[1]); }
.LBB0_1799:
	v_readlane_b32 s76, v242, 31
	v_readlane_b32 s77, v242, 32
	s_lshl_b32 s34, s0, 8
	s_add_u32 s34, s34, s48
	s_ashr_i32 s31, s0, 4
	s_mul_i32 s31, s31, 0x9000
	s_mov_b64 s[68:69], s[86:87]
	s_mov_b32 s35, s34
	s_add_u32 s70, s94, s31
	s_addc_u32 s71, s95, 0
	s_add_u32 s74, s70, 0x7000
	s_addc_u32 s75, s71, 0
	s_add_u32 s70, s70, 0x5000
	s_addc_u32 s71, s71, 0
	s_lshl_b32 s1, s30, 8
	s_or_b32 s1, s1, s49
	v_lshl_add_u32 v180, v220, 3, s1
	v_add_u32_e32 v181, s35, v147
	v_lshlrev_b32_e32 v243, 2, v180
	v_lshl_add_u32 v226, v181, 12, v243
	v_add_u32_e32 v182, s34, v147
	v_lshlrev_b32_e32 v183, 1, v180
	v_lshl_add_u32 v252, v182, 11, v183
	v_mov_b32_e32 v253, 0
	v_mov_b32_e32 v254, 0
	v_mov_b32_e32 v255, 0
	v_mov_b32_e32 v248, 0
	v_mov_b32_e32 v249, 0
	v_mov_b32_e32 v250, 0
	v_mov_b32_e32 v251, 0
	v_mov_b32_e32 v244, 0
	global_load_dwordx4 v[130:133], v243, s[70:71] offset:0
	global_load_dwordx4 v[134:137], v243, s[70:71] offset:16
	global_load_dwordx4 v[156:159], v243, s[70:71] offset:512
	global_load_dwordx4 v[160:163], v243, s[70:71] offset:528
	global_load_dwordx4 v[164:167], v243, s[76:77] offset:0
	global_load_dwordx4 v[168:171], v243, s[76:77] offset:16
	global_load_dwordx4 v[172:175], v243, s[76:77] offset:512
	global_load_dwordx4 v[176:179], v243, s[76:77] offset:528
	global_load_dwordx4 v[212:215], v243, s[74:75] offset:0
	global_load_dwordx4 v[216:219], v243, s[74:75] offset:16
	global_load_dwordx4 v[228:231], v243, s[74:75] offset:512
	global_load_dwordx4 v[232:235], v243, s[74:75] offset:528
	global_load_dwordx4 v[180:183], v226, s[68:69] offset:0
	global_load_dwordx4 v[184:187], v226, s[68:69] offset:16
	global_load_dwordx4 v[188:191], v226, s[68:69] offset:512
	global_load_dwordx4 v[192:195], v226, s[68:69] offset:528
	s_add_u32 s72, s68, 0x10000
	s_addc_u32 s73, s69, 0
	global_load_dwordx4 v[196:199], v226, s[72:73] offset:0
	global_load_dwordx4 v[200:203], v226, s[72:73] offset:16
	global_load_dwordx4 v[204:207], v226, s[72:73] offset:512
	global_load_dwordx4 v[208:211], v226, s[72:73] offset:528
	s_waitcnt vmcnt(8)
	v_pk_add_f32 v[212:213], v[212:213], 1.0 op_sel_hi:[1,0]
	v_pk_add_f32 v[214:215], v[214:215], 1.0 op_sel_hi:[1,0]
	v_pk_mul_f32 v[164:165], v[164:165], v[212:213]
	v_pk_mul_f32 v[166:167], v[166:167], v[214:215]
	v_pk_add_f32 v[216:217], v[216:217], 1.0 op_sel_hi:[1,0]
	v_pk_add_f32 v[218:219], v[218:219], 1.0 op_sel_hi:[1,0]
	v_pk_mul_f32 v[168:169], v[168:169], v[216:217]
	v_pk_mul_f32 v[170:171], v[170:171], v[218:219]
	v_pk_add_f32 v[228:229], v[228:229], 1.0 op_sel_hi:[1,0]
	v_pk_add_f32 v[230:231], v[230:231], 1.0 op_sel_hi:[1,0]
	v_pk_mul_f32 v[172:173], v[172:173], v[228:229]
	v_pk_mul_f32 v[174:175], v[174:175], v[230:231]
	v_pk_add_f32 v[232:233], v[232:233], 1.0 op_sel_hi:[1,0]
	v_pk_add_f32 v[234:235], v[234:235], 1.0 op_sel_hi:[1,0]
	v_pk_mul_f32 v[176:177], v[176:177], v[232:233]
	v_pk_mul_f32 v[178:179], v[178:179], v[234:235]
	s_add_u32 s72, s68, 0x20000
	s_addc_u32 s73, s69, 0
	global_load_dwordx4 v[212:215], v226, s[72:73] offset:0
	global_load_dwordx4 v[216:219], v226, s[72:73] offset:16
	global_load_dwordx4 v[228:231], v226, s[72:73] offset:512
	global_load_dwordx4 v[232:235], v226, s[72:73] offset:528
	s_waitcnt vmcnt(8)
	v_pk_fma_f32 v[126:127], v[126:127], v[130:131], v[180:181]
	v_pk_fma_f32 v[128:129], v[128:129], v[132:133], v[182:183]
	v_pk_fma_f32 v[122:123], v[122:123], v[134:135], v[184:185]
	v_pk_fma_f32 v[124:125], v[124:125], v[136:137], v[186:187]
	v_pk_fma_f32 v[66:67], v[66:67], v[156:157], v[188:189]
	v_pk_fma_f32 v[68:69], v[68:69], v[158:159], v[190:191]
	v_pk_fma_f32 v[58:59], v[58:59], v[160:161], v[192:193]
	v_pk_fma_f32 v[60:61], v[60:61], v[162:163], v[194:195]
	global_store_dwordx4 v226, v[126:129], s[68:69] offset:0
	global_store_dwordx4 v226, v[122:125], s[68:69] offset:16
	global_store_dwordx4 v226, v[66:69], s[68:69] offset:512
	global_store_dwordx4 v226, v[58:61], s[68:69] offset:528
	v_fmac_f32_e32 v253, v126, v126
	v_fmac_f32_e32 v253, v127, v127
	v_fmac_f32_e32 v253, v128, v128
	v_fmac_f32_e32 v253, v129, v129
	v_pk_mul_f32 v[180:181], v[126:127], v[164:165]
	v_pk_mul_f32 v[182:183], v[128:129], v[166:167]
	v_fmac_f32_e32 v253, v122, v122
	v_fmac_f32_e32 v253, v123, v123
	v_fmac_f32_e32 v253, v124, v124
	v_fmac_f32_e32 v253, v125, v125
	v_pk_mul_f32 v[184:185], v[122:123], v[168:169]
	v_pk_mul_f32 v[186:187], v[124:125], v[170:171]
	v_cvt_pk_bf16_f32 v180, v180, v181
	v_cvt_pk_bf16_f32 v181, v182, v183
	v_cvt_pk_bf16_f32 v182, v184, v185
	v_cvt_pk_bf16_f32 v183, v186, v187
	global_store_dwordx4 v252, v[180:183], s[60:61] offset:0
	v_fmac_f32_e32 v253, v66, v66
	v_fmac_f32_e32 v253, v67, v67
	v_fmac_f32_e32 v253, v68, v68
	v_fmac_f32_e32 v253, v69, v69
	v_pk_mul_f32 v[188:189], v[66:67], v[172:173]
	v_pk_mul_f32 v[190:191], v[68:69], v[174:175]
	v_fmac_f32_e32 v253, v58, v58
	v_fmac_f32_e32 v253, v59, v59
	v_fmac_f32_e32 v253, v60, v60
	v_fmac_f32_e32 v253, v61, v61
	v_pk_mul_f32 v[192:193], v[58:59], v[176:177]
	v_pk_mul_f32 v[194:195], v[60:61], v[178:179]
	v_cvt_pk_bf16_f32 v188, v188, v189
	v_cvt_pk_bf16_f32 v189, v190, v191
	v_cvt_pk_bf16_f32 v190, v192, v193
	v_cvt_pk_bf16_f32 v191, v194, v195
	global_store_dwordx4 v252, v[188:191], s[60:61] offset:256
	s_nop 0
	s_add_u32 s72, s68, 0x30000
	s_addc_u32 s73, s69, 0
	global_load_dwordx4 v[180:183], v226, s[72:73] offset:0
	global_load_dwordx4 v[184:187], v226, s[72:73] offset:16
	global_load_dwordx4 v[188:191], v226, s[72:73] offset:512
	global_load_dwordx4 v[192:195], v226, s[72:73] offset:528
	s_waitcnt vmcnt(14)
; DEV u32x4 pack8v(const f32x4 a, const f32x4 b) { u32x4 w; w.x = cvt_pk_bf16(a[0], a[1]); w.y = cvt_pk_bf16(a[2], a[3]); w.z = cvt_pk_bf16(b[0], b[1]); w.w = cvt_pk_bf16(b[2], b[3]); return w; }
;     DEV void operator()(const f32x4 (&acc)[2][2][4][2], const Unit& u, int wr, int wc, int fr, int fq) const {
;     ...
;             for (int ai = 0; ai < 2; ++ai)
; #pragma unroll
;                 for (int m = 0; m < 4; ++m) {
;                     const size_t p = (size_t)(row0 + ai * 128 + m * 16) * D + col0 + bj * 128;
;                     const f32x4 r0 = *(const f32x4*)(res + p), r1 = *(const f32x4*)(res + p + NS);
;                     const f32x4 o0 = r0 + gv[0] * acc[ai][bj][m][0], o1 = r1 + gv[1] * acc[ai][bj][m][1];
;                     *(f32x4*)(out + p) = o0; *(f32x4*)(out + p + NS) = o1;
;                     if (has_xn) { ss[ai * 4 + m] += (o0[0] * o0[0] + o0[1] * o0[1]) + (o0[2] * o0[2] + o0[3] * o0[3]) + (o1[0] * o1[0] + o1[1] * o1[1]) + (o1[2] * o1[2] + o1[3] * o1[3]);
;                         *(u32x4*)(xn + (size_t)(grow0 + ai * 128 + m * 16) * D + col0 + bj * 128) = pack8v(o0 * gs[0], o1 * gs[1]); }
	v_pk_fma_f32 v[118:119], v[118:119], v[130:131], v[196:197]
	v_pk_fma_f32 v[120:121], v[120:121], v[132:133], v[198:199]
	v_pk_fma_f32 v[114:115], v[114:115], v[134:135], v[200:201]
	v_pk_fma_f32 v[116:117], v[116:117], v[136:137], v[202:203]
	v_pk_fma_f32 v[54:55], v[54:55], v[156:157], v[204:205]
	v_pk_fma_f32 v[56:57], v[56:57], v[158:159], v[206:207]
	v_pk_fma_f32 v[50:51], v[50:51], v[160:161], v[208:209]
	v_pk_fma_f32 v[52:53], v[52:53], v[162:163], v[210:211]
	s_add_u32 s72, s68, 0x10000
	s_addc_u32 s73, s69, 0
	global_store_dwordx4 v226, v[118:121], s[72:73] offset:0
	global_store_dwordx4 v226, v[114:117], s[72:73] offset:16
	global_store_dwordx4 v226, v[54:57], s[72:73] offset:512
	global_store_dwordx4 v226, v[50:53], s[72:73] offset:528
	s_add_u32 s78, s60, 0x8000
	s_addc_u32 s79, s61, 0
	v_fmac_f32_e32 v254, v118, v118
	v_fmac_f32_e32 v254, v119, v119
	v_fmac_f32_e32 v254, v120, v120
	v_fmac_f32_e32 v254, v121, v121
	v_pk_mul_f32 v[196:197], v[118:119], v[164:165]
	v_pk_mul_f32 v[198:199], v[120:121], v[166:167]
	v_fmac_f32_e32 v254, v114, v114
	v_fmac_f32_e32 v254, v115, v115
	v_fmac_f32_e32 v254, v116, v116
	v_fmac_f32_e32 v254, v117, v117
	v_pk_mul_f32 v[200:201], v[114:115], v[168:169]
	v_pk_mul_f32 v[202:203], v[116:117], v[170:171]
	v_cvt_pk_bf16_f32 v196, v196, v197
	v_cvt_pk_bf16_f32 v197, v198, v199
	v_cvt_pk_bf16_f32 v198, v200, v201
	v_cvt_pk_bf16_f32 v199, v202, v203
	global_store_dwordx4 v252, v[196:199], s[78:79] offset:0
	v_fmac_f32_e32 v254, v54, v54
	v_fmac_f32_e32 v254, v55, v55
	v_fmac_f32_e32 v254, v56, v56
	v_fmac_f32_e32 v254, v57, v57
	v_pk_mul_f32 v[204:205], v[54:55], v[172:173]
	v_pk_mul_f32 v[206:207], v[56:57], v[174:175]
	v_fmac_f32_e32 v254, v50, v50
	v_fmac_f32_e32 v254, v51, v51
	v_fmac_f32_e32 v254, v52, v52
	v_fmac_f32_e32 v254, v53, v53
	v_pk_mul_f32 v[208:209], v[50:51], v[176:177]
	v_pk_mul_f32 v[210:211], v[52:53], v[178:179]
	v_cvt_pk_bf16_f32 v204, v204, v205
	v_cvt_pk_bf16_f32 v205, v206, v207
	v_cvt_pk_bf16_f32 v206, v208, v209
	v_cvt_pk_bf16_f32 v207, v210, v211
	global_store_dwordx4 v252, v[204:207], s[78:79] offset:256
	s_nop 0
	s_add_u32 s72, s68, 0x80000
	s_addc_u32 s73, s69, 0
	global_load_dwordx4 v[196:199], v226, s[72:73] offset:0
	global_load_dwordx4 v[200:203], v226, s[72:73] offset:16
	global_load_dwordx4 v[204:207], v226, s[72:73] offset:512
	global_load_dwordx4 v[208:211], v226, s[72:73] offset:528
	s_waitcnt vmcnt(20)
	v_pk_fma_f32 v[110:111], v[110:111], v[130:131], v[212:213]
	v_pk_fma_f32 v[112:113], v[112:113], v[132:133], v[214:215]
	v_pk_fma_f32 v[106:107], v[106:107], v[134:135], v[216:217]
	v_pk_fma_f32 v[108:109], v[108:109], v[136:137], v[218:219]
	v_pk_fma_f32 v[46:47], v[46:47], v[156:157], v[228:229]
	v_pk_fma_f32 v[48:49], v[48:49], v[158:159], v[230:231]
	v_pk_fma_f32 v[42:43], v[42:43], v[160:161], v[232:233]
	v_pk_fma_f32 v[44:45], v[44:45], v[162:163], v[234:235]
	s_add_u32 s72, s68, 0x20000
	s_addc_u32 s73, s69, 0
	global_store_dwordx4 v226, v[110:113], s[72:73] offset:0
	global_store_dwordx4 v226, v[106:109], s[72:73] offset:16
	global_store_dwordx4 v226, v[46:49], s[72:73] offset:512
	global_store_dwordx4 v226, v[42:45], s[72:73] offset:528
	s_add_u32 s78, s60, 0x10000
	s_addc_u32 s79, s61, 0
	v_fmac_f32_e32 v255, v110, v110
	v_fmac_f32_e32 v255, v111, v111
	v_fmac_f32_e32 v255, v112, v112
	v_fmac_f32_e32 v255, v113, v113
	v_pk_mul_f32 v[212:213], v[110:111], v[164:165]
	v_pk_mul_f32 v[214:215], v[112:113], v[166:167]
	v_fmac_f32_e32 v255, v106, v106
	v_fmac_f32_e32 v255, v107, v107
	v_fmac_f32_e32 v255, v108, v108
	v_fmac_f32_e32 v255, v109, v109
	v_pk_mul_f32 v[216:217], v[106:107], v[168:169]
	v_pk_mul_f32 v[218:219], v[108:109], v[170:171]
	v_cvt_pk_bf16_f32 v212, v212, v213
	v_cvt_pk_bf16_f32 v213, v214, v215
	v_cvt_pk_bf16_f32 v214, v216, v217
	v_cvt_pk_bf16_f32 v215, v218, v219
	global_store_dwordx4 v252, v[212:215], s[78:79] offset:0
	v_fmac_f32_e32 v255, v46, v46
	v_fmac_f32_e32 v255, v47, v47
	v_fmac_f32_e32 v255, v48, v48
	v_fmac_f32_e32 v255, v49, v49
	v_pk_mul_f32 v[228:229], v[46:47], v[172:173]
	v_pk_mul_f32 v[230:231], v[48:49], v[174:175]
	v_fmac_f32_e32 v255, v42, v42
	v_fmac_f32_e32 v255, v43, v43
	v_fmac_f32_e32 v255, v44, v44
	v_fmac_f32_e32 v255, v45, v45
	v_pk_mul_f32 v[232:233], v[42:43], v[176:177]
	v_pk_mul_f32 v[234:235], v[44:45], v[178:179]
	v_cvt_pk_bf16_f32 v228, v228, v229
	v_cvt_pk_bf16_f32 v229, v230, v231
	v_cvt_pk_bf16_f32 v230, v232, v233
	v_cvt_pk_bf16_f32 v231, v234, v235
	global_store_dwordx4 v252, v[228:231], s[78:79] offset:256
	s_nop 0
	s_add_u32 s72, s68, 0x90000
	s_addc_u32 s73, s69, 0
	global_load_dwordx4 v[212:215], v226, s[72:73] offset:0
	global_load_dwordx4 v[216:219], v226, s[72:73] offset:16
	global_load_dwordx4 v[228:231], v226, s[72:73] offset:512
	global_load_dwordx4 v[232:235], v226, s[72:73] offset:528
	s_waitcnt vmcnt(20)
; DEV u32x4 pack8v(const f32x4 a, const f32x4 b) { u32x4 w; w.x = cvt_pk_bf16(a[0], a[1]); w.y = cvt_pk_bf16(a[2], a[3]); w.z = cvt_pk_bf16(b[0], b[1]); w.w = cvt_pk_bf16(b[2], b[3]); return w; }
;     DEV void operator()(const f32x4 (&acc)[2][2][4][2], const Unit& u, int wr, int wc, int fr, int fq) const {
;     ...
;             for (int ai = 0; ai < 2; ++ai)
; #pragma unroll
;                 for (int m = 0; m < 4; ++m) {
;                     const size_t p = (size_t)(row0 + ai * 128 + m * 16) * D + col0 + bj * 128;
;                     const f32x4 r0 = *(const f32x4*)(res + p), r1 = *(const f32x4*)(res + p + NS);
;                     const f32x4 o0 = r0 + gv[0] * acc[ai][bj][m][0], o1 = r1 + gv[1] * acc[ai][bj][m][1];
;                     *(f32x4*)(out + p) = o0; *(f32x4*)(out + p + NS) = o1;
;                     if (has_xn) { ss[ai * 4 + m] += (o0[0] * o0[0] + o0[1] * o0[1]) + (o0[2] * o0[2] + o0[3] * o0[3]) + (o1[0] * o1[0] + o1[1] * o1[1]) + (o1[2] * o1[2] + o1[3] * o1[3]);
;                         *(u32x4*)(xn + (size_t)(grow0 + ai * 128 + m * 16) * D + col0 + bj * 128) = pack8v(o0 * gs[0], o1 * gs[1]); }
	v_pk_fma_f32 v[102:103], v[102:103], v[130:131], v[180:181]
	v_pk_fma_f32 v[104:105], v[104:105], v[132:133], v[182:183]
	v_pk_fma_f32 v[98:99], v[98:99], v[134:135], v[184:185]
	v_pk_fma_f32 v[100:101], v[100:101], v[136:137], v[186:187]
	v_pk_fma_f32 v[38:39], v[38:39], v[156:157], v[188:189]
	v_pk_fma_f32 v[40:41], v[40:41], v[158:159], v[190:191]
	v_pk_fma_f32 v[34:35], v[34:35], v[160:161], v[192:193]
	v_pk_fma_f32 v[36:37], v[36:37], v[162:163], v[194:195]
	s_add_u32 s72, s68, 0x30000
	s_addc_u32 s73, s69, 0
	global_store_dwordx4 v226, v[102:105], s[72:73] offset:0
	global_store_dwordx4 v226, v[98:101], s[72:73] offset:16
	global_store_dwordx4 v226, v[38:41], s[72:73] offset:512
	global_store_dwordx4 v226, v[34:37], s[72:73] offset:528
	s_add_u32 s78, s60, 0x18000
	s_addc_u32 s79, s61, 0
	v_fmac_f32_e32 v248, v102, v102
	v_fmac_f32_e32 v248, v103, v103
	v_fmac_f32_e32 v248, v104, v104
	v_fmac_f32_e32 v248, v105, v105
	v_pk_mul_f32 v[180:181], v[102:103], v[164:165]
	v_pk_mul_f32 v[182:183], v[104:105], v[166:167]
	v_fmac_f32_e32 v248, v98, v98
	v_fmac_f32_e32 v248, v99, v99
	v_fmac_f32_e32 v248, v100, v100
	v_fmac_f32_e32 v248, v101, v101
	v_pk_mul_f32 v[184:185], v[98:99], v[168:169]
	v_pk_mul_f32 v[186:187], v[100:101], v[170:171]
	v_cvt_pk_bf16_f32 v180, v180, v181
	v_cvt_pk_bf16_f32 v181, v182, v183
	v_cvt_pk_bf16_f32 v182, v184, v185
	v_cvt_pk_bf16_f32 v183, v186, v187
	global_store_dwordx4 v252, v[180:183], s[78:79] offset:0
	v_fmac_f32_e32 v248, v38, v38
	v_fmac_f32_e32 v248, v39, v39
	v_fmac_f32_e32 v248, v40, v40
	v_fmac_f32_e32 v248, v41, v41
	v_pk_mul_f32 v[188:189], v[38:39], v[172:173]
	v_pk_mul_f32 v[190:191], v[40:41], v[174:175]
	v_fmac_f32_e32 v248, v34, v34
	v_fmac_f32_e32 v248, v35, v35
	v_fmac_f32_e32 v248, v36, v36
	v_fmac_f32_e32 v248, v37, v37
	v_pk_mul_f32 v[192:193], v[34:35], v[176:177]
	v_pk_mul_f32 v[194:195], v[36:37], v[178:179]
	v_cvt_pk_bf16_f32 v188, v188, v189
	v_cvt_pk_bf16_f32 v189, v190, v191
	v_cvt_pk_bf16_f32 v190, v192, v193
	v_cvt_pk_bf16_f32 v191, v194, v195
	global_store_dwordx4 v252, v[188:191], s[78:79] offset:256
	s_nop 0
	s_add_u32 s72, s68, 0xa0000
	s_addc_u32 s73, s69, 0
	global_load_dwordx4 v[180:183], v226, s[72:73] offset:0
	global_load_dwordx4 v[184:187], v226, s[72:73] offset:16
	global_load_dwordx4 v[188:191], v226, s[72:73] offset:512
	global_load_dwordx4 v[192:195], v226, s[72:73] offset:528
	s_waitcnt vmcnt(20)
	v_pk_fma_f32 v[94:95], v[94:95], v[130:131], v[196:197]
	v_pk_fma_f32 v[96:97], v[96:97], v[132:133], v[198:199]
	v_pk_fma_f32 v[90:91], v[90:91], v[134:135], v[200:201]
	v_pk_fma_f32 v[92:93], v[92:93], v[136:137], v[202:203]
	v_pk_fma_f32 v[30:31], v[30:31], v[156:157], v[204:205]
	v_pk_fma_f32 v[32:33], v[32:33], v[158:159], v[206:207]
	v_pk_fma_f32 v[26:27], v[26:27], v[160:161], v[208:209]
	v_pk_fma_f32 v[28:29], v[28:29], v[162:163], v[210:211]
	s_add_u32 s72, s68, 0x80000
	s_addc_u32 s73, s69, 0
	global_store_dwordx4 v226, v[94:97], s[72:73] offset:0
	global_store_dwordx4 v226, v[90:93], s[72:73] offset:16
	global_store_dwordx4 v226, v[30:33], s[72:73] offset:512
	global_store_dwordx4 v226, v[26:29], s[72:73] offset:528
	s_add_u32 s78, s60, 0x40000
	s_addc_u32 s79, s61, 0
	v_fmac_f32_e32 v249, v94, v94
	v_fmac_f32_e32 v249, v95, v95
	v_fmac_f32_e32 v249, v96, v96
	v_fmac_f32_e32 v249, v97, v97
	v_pk_mul_f32 v[196:197], v[94:95], v[164:165]
	v_pk_mul_f32 v[198:199], v[96:97], v[166:167]
	v_fmac_f32_e32 v249, v90, v90
	v_fmac_f32_e32 v249, v91, v91
	v_fmac_f32_e32 v249, v92, v92
	v_fmac_f32_e32 v249, v93, v93
	v_pk_mul_f32 v[200:201], v[90:91], v[168:169]
	v_pk_mul_f32 v[202:203], v[92:93], v[170:171]
	v_cvt_pk_bf16_f32 v196, v196, v197
	v_cvt_pk_bf16_f32 v197, v198, v199
	v_cvt_pk_bf16_f32 v198, v200, v201
	v_cvt_pk_bf16_f32 v199, v202, v203
	global_store_dwordx4 v252, v[196:199], s[78:79] offset:0
	v_fmac_f32_e32 v249, v30, v30
	v_fmac_f32_e32 v249, v31, v31
	v_fmac_f32_e32 v249, v32, v32
	v_fmac_f32_e32 v249, v33, v33
	v_pk_mul_f32 v[204:205], v[30:31], v[172:173]
	v_pk_mul_f32 v[206:207], v[32:33], v[174:175]
	v_fmac_f32_e32 v249, v26, v26
	v_fmac_f32_e32 v249, v27, v27
	v_fmac_f32_e32 v249, v28, v28
	v_fmac_f32_e32 v249, v29, v29
	v_pk_mul_f32 v[208:209], v[26:27], v[176:177]
	v_pk_mul_f32 v[210:211], v[28:29], v[178:179]
	v_cvt_pk_bf16_f32 v204, v204, v205
	v_cvt_pk_bf16_f32 v205, v206, v207
	v_cvt_pk_bf16_f32 v206, v208, v209
	v_cvt_pk_bf16_f32 v207, v210, v211
	global_store_dwordx4 v252, v[204:207], s[78:79] offset:256
	s_nop 0
	s_add_u32 s72, s68, 0xb0000
	s_addc_u32 s73, s69, 0
	global_load_dwordx4 v[196:199], v226, s[72:73] offset:0
	global_load_dwordx4 v[200:203], v226, s[72:73] offset:16
	global_load_dwordx4 v[204:207], v226, s[72:73] offset:512
	global_load_dwordx4 v[208:211], v226, s[72:73] offset:528
	s_waitcnt vmcnt(20)
; DEV u32x4 pack8v(const f32x4 a, const f32x4 b) { u32x4 w; w.x = cvt_pk_bf16(a[0], a[1]); w.y = cvt_pk_bf16(a[2], a[3]); w.z = cvt_pk_bf16(b[0], b[1]); w.w = cvt_pk_bf16(b[2], b[3]); return w; }
;     DEV void operator()(const f32x4 (&acc)[2][2][4][2], const Unit& u, int wr, int wc, int fr, int fq) const {
;     ...
;             for (int ai = 0; ai < 2; ++ai)
; #pragma unroll
;                 for (int m = 0; m < 4; ++m) {
;                     const size_t p = (size_t)(row0 + ai * 128 + m * 16) * D + col0 + bj * 128;
;                     const f32x4 r0 = *(const f32x4*)(res + p), r1 = *(const f32x4*)(res + p + NS);
;                     const f32x4 o0 = r0 + gv[0] * acc[ai][bj][m][0], o1 = r1 + gv[1] * acc[ai][bj][m][1];
;                     *(f32x4*)(out + p) = o0; *(f32x4*)(out + p + NS) = o1;
;                     if (has_xn) { ss[ai * 4 + m] += (o0[0] * o0[0] + o0[1] * o0[1]) + (o0[2] * o0[2] + o0[3] * o0[3]) + (o1[0] * o1[0] + o1[1] * o1[1]) + (o1[2] * o1[2] + o1[3] * o1[3]);
;                         *(u32x4*)(xn + (size_t)(grow0 + ai * 128 + m * 16) * D + col0 + bj * 128) = pack8v(o0 * gs[0], o1 * gs[1]); }
	v_pk_fma_f32 v[86:87], v[86:87], v[130:131], v[212:213]
	v_pk_fma_f32 v[88:89], v[88:89], v[132:133], v[214:215]
	v_pk_fma_f32 v[82:83], v[82:83], v[134:135], v[216:217]
	v_pk_fma_f32 v[84:85], v[84:85], v[136:137], v[218:219]
	v_pk_fma_f32 v[22:23], v[22:23], v[156:157], v[228:229]
	v_pk_fma_f32 v[24:25], v[24:25], v[158:159], v[230:231]
	v_pk_fma_f32 v[18:19], v[18:19], v[160:161], v[232:233]
	v_pk_fma_f32 v[20:21], v[20:21], v[162:163], v[234:235]
	s_add_u32 s72, s68, 0x90000
	s_addc_u32 s73, s69, 0
	global_store_dwordx4 v226, v[86:89], s[72:73] offset:0
	global_store_dwordx4 v226, v[82:85], s[72:73] offset:16
	global_store_dwordx4 v226, v[22:25], s[72:73] offset:512
	global_store_dwordx4 v226, v[18:21], s[72:73] offset:528
	s_add_u32 s78, s60, 0x48000
	s_addc_u32 s79, s61, 0
	v_fmac_f32_e32 v250, v86, v86
	v_fmac_f32_e32 v250, v87, v87
	v_fmac_f32_e32 v250, v88, v88
	v_fmac_f32_e32 v250, v89, v89
	v_pk_mul_f32 v[212:213], v[86:87], v[164:165]
	v_pk_mul_f32 v[214:215], v[88:89], v[166:167]
	v_fmac_f32_e32 v250, v82, v82
	v_fmac_f32_e32 v250, v83, v83
	v_fmac_f32_e32 v250, v84, v84
	v_fmac_f32_e32 v250, v85, v85
	v_pk_mul_f32 v[216:217], v[82:83], v[168:169]
	v_pk_mul_f32 v[218:219], v[84:85], v[170:171]
	v_cvt_pk_bf16_f32 v212, v212, v213
	v_cvt_pk_bf16_f32 v213, v214, v215
	v_cvt_pk_bf16_f32 v214, v216, v217
	v_cvt_pk_bf16_f32 v215, v218, v219
	global_store_dwordx4 v252, v[212:215], s[78:79] offset:0
	v_fmac_f32_e32 v250, v22, v22
	v_fmac_f32_e32 v250, v23, v23
	v_fmac_f32_e32 v250, v24, v24
	v_fmac_f32_e32 v250, v25, v25
	v_pk_mul_f32 v[228:229], v[22:23], v[172:173]
	v_pk_mul_f32 v[230:231], v[24:25], v[174:175]
	v_fmac_f32_e32 v250, v18, v18
	v_fmac_f32_e32 v250, v19, v19
	v_fmac_f32_e32 v250, v20, v20
	v_fmac_f32_e32 v250, v21, v21
	v_pk_mul_f32 v[232:233], v[18:19], v[176:177]
	v_pk_mul_f32 v[234:235], v[20:21], v[178:179]
	v_cvt_pk_bf16_f32 v228, v228, v229
	v_cvt_pk_bf16_f32 v229, v230, v231
	v_cvt_pk_bf16_f32 v230, v232, v233
	v_cvt_pk_bf16_f32 v231, v234, v235
	global_store_dwordx4 v252, v[228:231], s[78:79] offset:256
	s_nop 0
	s_waitcnt vmcnt(16)
	v_pk_fma_f32 v[78:79], v[78:79], v[130:131], v[180:181]
	v_pk_fma_f32 v[80:81], v[80:81], v[132:133], v[182:183]
	v_pk_fma_f32 v[74:75], v[74:75], v[134:135], v[184:185]
	v_pk_fma_f32 v[76:77], v[76:77], v[136:137], v[186:187]
	v_pk_fma_f32 v[14:15], v[14:15], v[156:157], v[188:189]
	v_pk_fma_f32 v[16:17], v[16:17], v[158:159], v[190:191]
	v_pk_fma_f32 v[10:11], v[10:11], v[160:161], v[192:193]
	v_pk_fma_f32 v[12:13], v[12:13], v[162:163], v[194:195]
	s_add_u32 s72, s68, 0xa0000
	s_addc_u32 s73, s69, 0
	global_store_dwordx4 v226, v[78:81], s[72:73] offset:0
	global_store_dwordx4 v226, v[74:77], s[72:73] offset:16
	global_store_dwordx4 v226, v[14:17], s[72:73] offset:512
	global_store_dwordx4 v226, v[10:13], s[72:73] offset:528
	s_add_u32 s78, s60, 0x50000
	s_addc_u32 s79, s61, 0
	v_fmac_f32_e32 v251, v78, v78
	v_fmac_f32_e32 v251, v79, v79
	v_fmac_f32_e32 v251, v80, v80
	v_fmac_f32_e32 v251, v81, v81
	v_pk_mul_f32 v[180:181], v[78:79], v[164:165]
	v_pk_mul_f32 v[182:183], v[80:81], v[166:167]
	v_fmac_f32_e32 v251, v74, v74
	v_fmac_f32_e32 v251, v75, v75
	v_fmac_f32_e32 v251, v76, v76
	v_fmac_f32_e32 v251, v77, v77
	v_pk_mul_f32 v[184:185], v[74:75], v[168:169]
	v_pk_mul_f32 v[186:187], v[76:77], v[170:171]
	v_cvt_pk_bf16_f32 v180, v180, v181
	v_cvt_pk_bf16_f32 v181, v182, v183
	v_cvt_pk_bf16_f32 v182, v184, v185
	v_cvt_pk_bf16_f32 v183, v186, v187
	global_store_dwordx4 v252, v[180:183], s[78:79] offset:0
	v_fmac_f32_e32 v251, v14, v14
	v_fmac_f32_e32 v251, v15, v15
	v_fmac_f32_e32 v251, v16, v16
	v_fmac_f32_e32 v251, v17, v17
	v_pk_mul_f32 v[188:189], v[14:15], v[172:173]
	v_pk_mul_f32 v[190:191], v[16:17], v[174:175]
	v_fmac_f32_e32 v251, v10, v10
	v_fmac_f32_e32 v251, v11, v11
	v_fmac_f32_e32 v251, v12, v12
	v_fmac_f32_e32 v251, v13, v13
	v_pk_mul_f32 v[192:193], v[10:11], v[176:177]
	v_pk_mul_f32 v[194:195], v[12:13], v[178:179]
	v_cvt_pk_bf16_f32 v188, v188, v189
	v_cvt_pk_bf16_f32 v189, v190, v191
	v_cvt_pk_bf16_f32 v190, v192, v193
	v_cvt_pk_bf16_f32 v191, v194, v195
	global_store_dwordx4 v252, v[188:191], s[78:79] offset:256
	s_nop 0
	s_waitcnt vmcnt(12)
; DEV u32x4 pack8v(const f32x4 a, const f32x4 b) { u32x4 w; w.x = cvt_pk_bf16(a[0], a[1]); w.y = cvt_pk_bf16(a[2], a[3]); w.z = cvt_pk_bf16(b[0], b[1]); w.w = cvt_pk_bf16(b[2], b[3]); return w; }
;     DEV void operator()(const f32x4 (&acc)[2][2][4][2], const Unit& u, int wr, int wc, int fr, int fq) const {
;     ...
;             for (int ai = 0; ai < 2; ++ai)
; #pragma unroll
;                 for (int m = 0; m < 4; ++m) {
;                     const size_t p = (size_t)(row0 + ai * 128 + m * 16) * D + col0 + bj * 128;
;                     const f32x4 r0 = *(const f32x4*)(res + p), r1 = *(const f32x4*)(res + p + NS);
;                     const f32x4 o0 = r0 + gv[0] * acc[ai][bj][m][0], o1 = r1 + gv[1] * acc[ai][bj][m][1];
;                     *(f32x4*)(out + p) = o0; *(f32x4*)(out + p + NS) = o1;
;                     if (has_xn) { ss[ai * 4 + m] += (o0[0] * o0[0] + o0[1] * o0[1]) + (o0[2] * o0[2] + o0[3] * o0[3]) + (o1[0] * o1[0] + o1[1] * o1[1]) + (o1[2] * o1[2] + o1[3] * o1[3]);
;                         *(u32x4*)(xn + (size_t)(grow0 + ai * 128 + m * 16) * D + col0 + bj * 128) = pack8v(o0 * gs[0], o1 * gs[1]); }
;     ...
;         if (has_xn) {
; #pragma unroll
;             for (int i = 0; i < 8; ++i) { float v = ss[i]; v += __shfl_xor(v, 16); v += __shfl_xor(v, 32); if (fq == 0) rs[(size_t)(grow0 + (i >> 2) * 128 + (i & 3) * 16) * 16 + u.pn * 4 + wc] = v; }
;         }
	v_pk_fma_f32 v[70:71], v[70:71], v[130:131], v[196:197]
	v_pk_fma_f32 v[72:73], v[72:73], v[132:133], v[198:199]
	v_pk_fma_f32 v[62:63], v[62:63], v[134:135], v[200:201]
	v_pk_fma_f32 v[64:65], v[64:65], v[136:137], v[202:203]
	v_pk_fma_f32 v[6:7], v[6:7], v[156:157], v[204:205]
	v_pk_fma_f32 v[8:9], v[8:9], v[158:159], v[206:207]
	v_pk_fma_f32 v[2:3], v[2:3], v[160:161], v[208:209]
	v_pk_fma_f32 v[4:5], v[4:5], v[162:163], v[210:211]
	s_add_u32 s72, s68, 0xb0000
	s_addc_u32 s73, s69, 0
	global_store_dwordx4 v226, v[70:73], s[72:73] offset:0
	global_store_dwordx4 v226, v[62:65], s[72:73] offset:16
	global_store_dwordx4 v226, v[6:9], s[72:73] offset:512
	global_store_dwordx4 v226, v[2:5], s[72:73] offset:528
	s_add_u32 s78, s60, 0x58000
	s_addc_u32 s79, s61, 0
	v_fmac_f32_e32 v244, v70, v70
	v_fmac_f32_e32 v244, v71, v71
	v_fmac_f32_e32 v244, v72, v72
	v_fmac_f32_e32 v244, v73, v73
	v_pk_mul_f32 v[196:197], v[70:71], v[164:165]
	v_pk_mul_f32 v[198:199], v[72:73], v[166:167]
	v_fmac_f32_e32 v244, v62, v62
	v_fmac_f32_e32 v244, v63, v63
	v_fmac_f32_e32 v244, v64, v64
	v_fmac_f32_e32 v244, v65, v65
	v_pk_mul_f32 v[200:201], v[62:63], v[168:169]
	v_pk_mul_f32 v[202:203], v[64:65], v[170:171]
	v_cvt_pk_bf16_f32 v196, v196, v197
	v_cvt_pk_bf16_f32 v197, v198, v199
	v_cvt_pk_bf16_f32 v198, v200, v201
	v_cvt_pk_bf16_f32 v199, v202, v203
	global_store_dwordx4 v252, v[196:199], s[78:79] offset:0
	v_fmac_f32_e32 v244, v6, v6
	v_fmac_f32_e32 v244, v7, v7
	v_fmac_f32_e32 v244, v8, v8
	v_fmac_f32_e32 v244, v9, v9
	v_pk_mul_f32 v[204:205], v[6:7], v[172:173]
	v_pk_mul_f32 v[206:207], v[8:9], v[174:175]
	v_fmac_f32_e32 v244, v2, v2
	v_fmac_f32_e32 v244, v3, v3
	v_fmac_f32_e32 v244, v4, v4
	v_fmac_f32_e32 v244, v5, v5
	v_pk_mul_f32 v[208:209], v[2:3], v[176:177]
	v_pk_mul_f32 v[210:211], v[4:5], v[178:179]
	v_cvt_pk_bf16_f32 v204, v204, v205
	v_cvt_pk_bf16_f32 v205, v206, v207
	v_cvt_pk_bf16_f32 v206, v208, v209
	v_cvt_pk_bf16_f32 v207, v210, v211
	global_store_dwordx4 v252, v[204:207], s[78:79] offset:256
	s_nop 0
	s_nop 1
	v_xor_b32_e32 v180, 16, v225
	v_xor_b32_e32 v181, 32, v225
	v_lshlrev_b32_e32 v180, 2, v180
	v_lshlrev_b32_e32 v181, 2, v181
	ds_bpermute_b32 v196, v180, v253
	ds_bpermute_b32 v197, v180, v254
	ds_bpermute_b32 v198, v180, v255
	ds_bpermute_b32 v199, v180, v248
	ds_bpermute_b32 v200, v180, v249
	ds_bpermute_b32 v201, v180, v250
	ds_bpermute_b32 v202, v180, v251
	ds_bpermute_b32 v203, v180, v244
	s_waitcnt lgkmcnt(0)
	v_add_f32_e32 v253, v253, v196
	v_add_f32_e32 v254, v254, v197
	v_add_f32_e32 v255, v255, v198
	v_add_f32_e32 v248, v248, v199
	v_add_f32_e32 v249, v249, v200
	v_add_f32_e32 v250, v250, v201
	v_add_f32_e32 v251, v251, v202
	v_add_f32_e32 v244, v244, v203
	ds_bpermute_b32 v196, v181, v253
	ds_bpermute_b32 v197, v181, v254
	ds_bpermute_b32 v198, v181, v255
	ds_bpermute_b32 v199, v181, v248
	ds_bpermute_b32 v200, v181, v249
	ds_bpermute_b32 v201, v181, v250
	ds_bpermute_b32 v202, v181, v251
	ds_bpermute_b32 v203, v181, v244
	s_waitcnt lgkmcnt(0)
	v_add_f32_e32 v253, v253, v196
	v_add_f32_e32 v254, v254, v197
	v_add_f32_e32 v255, v255, v198
	v_add_f32_e32 v248, v248, v199
	v_add_f32_e32 v249, v249, v200
	v_add_f32_e32 v250, v250, v201
	v_add_f32_e32 v251, v251, v202
	v_add_f32_e32 v244, v244, v203
	v_add_u32_e32 v182, s34, v147
	v_lshlrev_b32_e32 v182, 6, v182
	s_lshl_b32 s1, s30, 4
	s_add_u32 s72, s55, s1
	s_addc_u32 s73, s58, 0
	s_add_u32 s78, s72, 0x2000
	s_addc_u32 s79, s73, 0
	v_cmp_eq_u32_e32 vcc, 0, v220
	s_nop 4
	s_and_saveexec_b64 s[80:81], vcc
	v_lshrrev_b32_e32 v182, 4, v182
	s_add_u32 s72, s88, 0x3ce00000
	s_addc_u32 s73, s89, 0
	global_atomic_add_f32 v182, v253, s[72:73] offset:0
	global_atomic_add_f32 v182, v254, s[72:73] offset:64
	global_atomic_add_f32 v182, v255, s[72:73] offset:128
	global_atomic_add_f32 v182, v248, s[72:73] offset:192
	global_atomic_add_f32 v182, v249, s[72:73] offset:512
	global_atomic_add_f32 v182, v250, s[72:73] offset:576
	global_atomic_add_f32 v182, v251, s[72:73] offset:640
	global_atomic_add_f32 v182, v244, s[72:73] offset:704
	s_or_b64 exec, exec, s[80:81]
	s_andn2_b64 vcc, exec, s[4:5]
	s_mov_b64 s[0:1], -1
	s_cbranch_vccnz .LBB0_1788
	s_andn2_b64 vcc, exec, s[8:9]
	s_cbranch_vccnz .LBB0_1787
	s_barrier
	s_branch .LBB0_1787

;     __host__ __device__ bool next(int i, Unit& u) const {
;         const long L = (long)i * G + c; if (L >= nwg) return false;
;         int wgid = (int)L; { const int q = nwg / NXCD, r = nwg % NXCD, xcd = wgid % NXCD, off = wgid / NXCD; wgid = (xcd < r ? xcd * (q + 1) : r * (q + 1) + (xcd - r) * q) + off; }
;         const int nig = WGM * nN, gid = wgid / nig, fm = gid * WGM, gsz = (nM - fm) < WGM ? (nM - fm) : WGM;
;         u.pm = fm + ((wgid % nig) % gsz); u.pn = (wgid % nig) / gsz; return true;
;     DEV void operator()(const f32x4 (&acc)[2][2][4][2], const Unit& u, int wr, int wc, int fr, int fq) const {
;         asm volatile("" : "+v"(fr), "+v"(fq));
;         const int row0 = u.pm * 256 + wr * 64 + fr, col0 = u.pn * 128 + wc * 32 + 8 * fq;
;         f32x4 sg[2], su[2];
;         if (FUSED) { const int b = u.pm >> 4; const float* sp = shw + (size_t)b * NFF2 + u.pn * 256 + wc * 32 + 8 * fq;
;             sg[0] = *(const f32x4*)sp; sg[1] = *(const f32x4*)(sp + 4); su[0] = *(const f32x4*)(sp + 128); su[1] = *(const f32x4*)(sp + 132); }
;         float rstd8[8];
;         if (FUSED) row_rstd8(rs, row0, fq, rstd8);
.LBB0_1892:
	s_lshl_b32 s100, s0, 8
	s_add_u32 s100, s100, s44
	v_add_u32_e32 v252, s100, v147
	v_lshlrev_b32_e32 v252, 2, v252
	s_add_u32 s98, s88, 0x3ce00000
	s_addc_u32 s99, s89, 0
	global_load_dword v243, v252, s[98:99] offset:0
	global_load_dword v244, v252, s[98:99] offset:64
	global_load_dword v245, v252, s[98:99] offset:128
	global_load_dword v246, v252, s[98:99] offset:192
	global_load_dword v247, v252, s[98:99] offset:512
	global_load_dword v248, v252, s[98:99] offset:576
	global_load_dword v249, v252, s[98:99] offset:640
	global_load_dword v250, v252, s[98:99] offset:704
	s_ashr_i32 s100, s0, 4
	s_mul_i32 s100, s100, 0x5800
	s_lshl_b32 s101, s1, 10
	s_add_u32 s100, s100, s101
	s_lshl_b32 s101, s45, 2
	s_add_u32 s100, s100, s101
	s_add_u32 s98, s88, 0x3d300000
	s_addc_u32 s99, s89, 0
	s_add_u32 s98, s98, s100
	s_addc_u32 s99, s99, 0
	v_and_b32_e32 v253, 31, v191
	v_lshrrev_b32_e32 v254, 5, v191
	v_lshl_add_u32 v253, v254, 7, v253
	v_lshlrev_b32_e32 v253, 2, v253
	global_load_dword v251, v253, s[98:99]
	s_add_i32 s41, s41, 1
	s_mul_i32 s4, s41, s48
	s_mul_hi_u32 s5, s41, s50
	s_add_i32 s5, s5, s4
	s_mul_i32 s4, s41, s50
	s_add_u32 s26, s4, s2
	s_addc_u32 s27, s5, s33
	v_cmp_gt_i64_e32 vcc, s[26:27], v[162:163]
	v_cmp_lt_i64_e64 s[4:5], s[26:27], v[160:161]
	s_cbranch_vccnz .LBB0_1894
	s_ashr_i32 s22, s26, 31
	s_lshr_b32 s22, s22, 29
	s_add_i32 s22, s26, s22
	s_ashr_i32 s23, s22, 3
	s_and_b32 s22, s22, -8
	s_sub_i32 s22, s26, s22
	s_cmp_lt_i32 s22, 0
	s_cselect_b32 s24, s36, 0x2c0
	s_mul_i32 s22, s22, s24
	s_add_i32 s22, s22, s23
	s_mul_hi_i32 s23, s22, 0x2e8ba2e9
	s_lshr_b32 s24, s23, 31
	s_ashr_i32 s23, s23, 5
	s_add_i32 s23, s23, s24
	s_lshl_b32 s24, s23, 3
	s_sub_i32 s25, 0x100, s24
	s_min_i32 s25, s25, 8
	s_abs_i32 s26, s25
	v_cvt_f32_u32_e32 v2, s26
	s_sub_i32 s28, 0, s26
	s_mulk_i32 s23, 0xb0
	s_sub_i32 s23, s22, s23
	v_rcp_iflag_f32_e32 v2, v2
	s_abs_i32 s22, s23
	s_xor_b32 s27, s23, s25
	s_ashr_i32 s27, s27, 31
	v_mul_f32_e32 v2, 0x4f7ffffe, v2
	v_cvt_u32_f32_e32 v2, v2
	s_nop 0
	v_readfirstlane_b32 s29, v2
	s_mul_i32 s28, s28, s29
	s_mul_hi_u32 s28, s29, s28
	s_add_i32 s29, s29, s28
	s_mul_hi_u32 s28, s22, s29
	s_mul_i32 s29, s28, s26
	s_sub_i32 s22, s22, s29
	s_add_i32 s34, s28, 1
	s_sub_i32 s29, s22, s26
	s_cmp_ge_u32 s22, s26
	s_cselect_b32 s28, s34, s28
	s_cselect_b32 s22, s29, s22
	s_add_i32 s29, s28, 1
	s_cmp_ge_u32 s22, s26
	s_cselect_b32 s22, s29, s28
	s_xor_b32 s22, s22, s27
	s_sub_i32 s22, s22, s27
	s_mul_i32 s25, s22, s25
	s_sub_i32 s23, s23, s25
	s_add_i32 s24, s24, s23

; DEV float silu_f(float x) { return x * __builtin_amdgcn_rcpf(1.f + __expf(-x)); }
; DEV u32x4 pack8(const float (&f)[8]) { u32x4 w; w.x = cvt_pk_bf16(f[0], f[1]); w.y = cvt_pk_bf16(f[2], f[3]); w.z = cvt_pk_bf16(f[4], f[5]); w.w = cvt_pk_bf16(f[6], f[7]); return w; }
;     DEV void operator()(const f32x4 (&acc)[2][2][4][2], const Unit& u, int wr, int wc, int fr, int fq) const {
;         asm volatile("" : "+v"(fr), "+v"(fq));
;         const int row0 = u.pm * 256 + wr * 64 + fr, col0 = u.pn * 128 + wc * 32 + 8 * fq;
;         f32x4 sg[2], su[2];
;         if (FUSED) { const int b = u.pm >> 4; const float* sp = shw + (size_t)b * NFF2 + u.pn * 256 + wc * 32 + 8 * fq;
;             sg[0] = *(const f32x4*)sp; sg[1] = *(const f32x4*)(sp + 4); su[0] = *(const f32x4*)(sp + 128); su[1] = *(const f32x4*)(sp + 132); }
;         float rstd8[8];
;         if (FUSED) row_rstd8(rs, row0, fq, rstd8);
; #pragma unroll
;         for (int ai = 0; ai < 2; ++ai)
; #pragma unroll
;             for (int m = 0; m < 4; ++m) {
;                 const int row = row0 + ai * 128 + m * 16;
;                 const float rstd = FUSED ? rstd8[ai * 4 + m] : 1.f;
;                 float h[8];
; #pragma unroll
;                 for (int n = 0; n < 2; ++n)
; #pragma unroll
;                     for (int j = 0; j < 4; ++j) { float g = acc[ai][0][m][n][j], up = acc[ai][1][m][n][j]; if (FUSED) { g = g * rstd + sg[n][j]; up = up * rstd + su[n][j]; } h[4 * n + j] = silu_f(g) * up; }
;                 *(u32x4*)(H + (size_t)row * DFF + col0) = pack8(h);
;             }
.LBB0_1898:
	s_waitcnt vmcnt(8)
	v_mov_b32_e32 v200, 0x358637bd
	s_mov_b32 s6, 0x3a800000
	v_fma_f32 v243, v243, s6, v200
	v_fma_f32 v244, v244, s6, v200
	v_fma_f32 v245, v245, s6, v200
	v_fma_f32 v246, v246, s6, v200
	v_fma_f32 v247, v247, s6, v200
	v_fma_f32 v248, v248, s6, v200
	v_fma_f32 v249, v249, s6, v200
	v_fma_f32 v250, v250, s6, v200
	v_rsq_f32_e32 v243, v243
	v_rsq_f32_e32 v244, v244
	v_rsq_f32_e32 v245, v245
	v_rsq_f32_e32 v246, v246
	v_rsq_f32_e32 v247, v247
	v_rsq_f32_e32 v248, v248
	v_rsq_f32_e32 v249, v249
	v_rsq_f32_e32 v250, v250
	s_lshl_b32 s7, s44, 4
	s_lshl_b32 s6, s45, 3
	s_add_u32 s7, s7, s6
	s_add_u32 s7, s7, 0x20000
	v_lshl_add_u32 v201, v191, 2, s7
	ds_write_b32 v201, v251
	v_lshl_add_u32 v202, v171, 5, s7
	s_lshl_b32 s23, s0, 8
	s_add_u32 s23, s23, s44
	s_lshl_b32 s6, s1, 7
	s_or_b32 s6, s6, s45
	v_add_u32_e32 v203, s23, v147
	v_mul_u32_u24_e32 v204, 0x1600, v203
	v_lshl_add_u32 v205, v171, 3, s6
	v_lshl_add_u32 v204, v205, 1, v204
	s_waitcnt lgkmcnt(0)
	ds_read_b128 v[130:133], v202
	ds_read_b128 v[134:137], v202 offset:16
	ds_read_b128 v[138:141], v202 offset:128
	ds_read_b128 v[142:145], v202 offset:144
	s_waitcnt lgkmcnt(0)
	v_fma_f32 v126, v126, v243, v130
	v_fma_f32 v127, v127, v243, v131
	v_fma_f32 v128, v128, v243, v132
	v_fma_f32 v129, v129, v243, v133
	v_fma_f32 v122, v122, v243, v134
	v_fma_f32 v123, v123, v243, v135
	v_fma_f32 v124, v124, v243, v136
	v_fma_f32 v125, v125, v243, v137
	v_mul_f32_e32 v192, 0xbfb8aa3b, v126
	v_mul_f32_e32 v193, 0xbfb8aa3b, v127
	v_mul_f32_e32 v194, 0xbfb8aa3b, v128
	v_mul_f32_e32 v195, 0xbfb8aa3b, v129
	v_mul_f32_e32 v196, 0xbfb8aa3b, v122
	v_mul_f32_e32 v197, 0xbfb8aa3b, v123
	v_mul_f32_e32 v198, 0xbfb8aa3b, v124
	v_mul_f32_e32 v199, 0xbfb8aa3b, v125
	v_exp_f32_e32 v192, v192
	v_exp_f32_e32 v193, v193
	v_exp_f32_e32 v194, v194
	v_exp_f32_e32 v195, v195
	v_exp_f32_e32 v196, v196
	v_exp_f32_e32 v197, v197
	v_exp_f32_e32 v198, v198
	v_exp_f32_e32 v199, v199
	v_fma_f32 v118, v118, v243, v138
	v_fma_f32 v119, v119, v243, v139
	v_fma_f32 v120, v120, v243, v140
	v_fma_f32 v121, v121, v243, v141
	v_fma_f32 v114, v114, v243, v142
	v_fma_f32 v115, v115, v243, v143
	v_fma_f32 v116, v116, v243, v144
	v_fma_f32 v117, v117, v243, v145
	v_add_f32_e32 v192, 1.0, v192
	v_add_f32_e32 v193, 1.0, v193
	v_add_f32_e32 v194, 1.0, v194
	v_add_f32_e32 v195, 1.0, v195
	v_add_f32_e32 v196, 1.0, v196
	v_add_f32_e32 v197, 1.0, v197
	v_add_f32_e32 v198, 1.0, v198
	v_add_f32_e32 v199, 1.0, v199
	v_rcp_f32_e32 v192, v192
	v_rcp_f32_e32 v193, v193
	v_rcp_f32_e32 v194, v194
	v_rcp_f32_e32 v195, v195
	v_rcp_f32_e32 v196, v196
	v_rcp_f32_e32 v197, v197
	v_rcp_f32_e32 v198, v198
	v_rcp_f32_e32 v199, v199
	v_mul_f32_e32 v126, v126, v118
	v_mul_f32_e32 v127, v127, v119
	v_mul_f32_e32 v128, v128, v120
	v_mul_f32_e32 v129, v129, v121
	v_mul_f32_e32 v122, v122, v114
	v_mul_f32_e32 v123, v123, v115
	v_mul_f32_e32 v124, v124, v116
	v_mul_f32_e32 v125, v125, v117
	v_mul_f32_e32 v126, v126, v192
	v_mul_f32_e32 v127, v127, v193
	v_mul_f32_e32 v128, v128, v194
	v_mul_f32_e32 v129, v129, v195
	v_mul_f32_e32 v122, v122, v196
	v_mul_f32_e32 v123, v123, v197
	v_mul_f32_e32 v124, v124, v198
	v_mul_f32_e32 v125, v125, v199
	v_cvt_pk_bf16_f32 v118, v126, v127
	v_cvt_pk_bf16_f32 v119, v128, v129
	v_cvt_pk_bf16_f32 v120, v122, v123
	v_cvt_pk_bf16_f32 v121, v124, v125
	global_store_dwordx4 v204, v[118:121], s[56:57]
	v_fma_f32 v110, v110, v244, v130
	v_fma_f32 v111, v111, v244, v131
	v_fma_f32 v112, v112, v244, v132
	v_fma_f32 v113, v113, v244, v133
	v_fma_f32 v106, v106, v244, v134
	v_fma_f32 v107, v107, v244, v135
	v_fma_f32 v108, v108, v244, v136
	v_fma_f32 v109, v109, v244, v137
	v_mul_f32_e32 v192, 0xbfb8aa3b, v110
	v_mul_f32_e32 v193, 0xbfb8aa3b, v111
	v_mul_f32_e32 v194, 0xbfb8aa3b, v112
	v_mul_f32_e32 v195, 0xbfb8aa3b, v113
	v_mul_f32_e32 v196, 0xbfb8aa3b, v106
	v_mul_f32_e32 v197, 0xbfb8aa3b, v107
	v_mul_f32_e32 v198, 0xbfb8aa3b, v108
	v_mul_f32_e32 v199, 0xbfb8aa3b, v109
	v_exp_f32_e32 v192, v192
	v_exp_f32_e32 v193, v193
	v_exp_f32_e32 v194, v194
	v_exp_f32_e32 v195, v195
	v_exp_f32_e32 v196, v196
	v_exp_f32_e32 v197, v197
	v_exp_f32_e32 v198, v198
	v_exp_f32_e32 v199, v199
	v_fma_f32 v102, v102, v244, v138
	v_fma_f32 v103, v103, v244, v139
	v_fma_f32 v104, v104, v244, v140
	v_fma_f32 v105, v105, v244, v141
	v_fma_f32 v98, v98, v244, v142
	v_fma_f32 v99, v99, v244, v143
	v_fma_f32 v100, v100, v244, v144
	v_fma_f32 v101, v101, v244, v145
	v_add_f32_e32 v192, 1.0, v192
	v_add_f32_e32 v193, 1.0, v193
	v_add_f32_e32 v194, 1.0, v194
	v_add_f32_e32 v195, 1.0, v195
	v_add_f32_e32 v196, 1.0, v196
	v_add_f32_e32 v197, 1.0, v197
	v_add_f32_e32 v198, 1.0, v198
	v_add_f32_e32 v199, 1.0, v199
	v_rcp_f32_e32 v192, v192
	v_rcp_f32_e32 v193, v193
	v_rcp_f32_e32 v194, v194
	v_rcp_f32_e32 v195, v195
	v_rcp_f32_e32 v196, v196
	v_rcp_f32_e32 v197, v197
	v_rcp_f32_e32 v198, v198
	v_rcp_f32_e32 v199, v199
	v_mul_f32_e32 v110, v110, v102
	v_mul_f32_e32 v111, v111, v103
	v_mul_f32_e32 v112, v112, v104
	v_mul_f32_e32 v113, v113, v105
	v_mul_f32_e32 v106, v106, v98
	v_mul_f32_e32 v107, v107, v99
	v_mul_f32_e32 v108, v108, v100
	v_mul_f32_e32 v109, v109, v101
	v_mul_f32_e32 v110, v110, v192
	v_mul_f32_e32 v111, v111, v193
	v_mul_f32_e32 v112, v112, v194
	v_mul_f32_e32 v113, v113, v195
	v_mul_f32_e32 v106, v106, v196
	v_mul_f32_e32 v107, v107, v197
	v_mul_f32_e32 v108, v108, v198
	v_mul_f32_e32 v109, v109, v199
	v_cvt_pk_bf16_f32 v102, v110, v111
	v_cvt_pk_bf16_f32 v103, v112, v113
	v_cvt_pk_bf16_f32 v104, v106, v107
	v_cvt_pk_bf16_f32 v105, v108, v109
	s_add_u32 s98, s56, 0x16000
	s_addc_u32 s99, s57, 0
	global_store_dwordx4 v204, v[102:105], s[98:99]
; DEV float silu_f(float x) { return x * __builtin_amdgcn_rcpf(1.f + __expf(-x)); }
; DEV u32x4 pack8(const float (&f)[8]) { u32x4 w; w.x = cvt_pk_bf16(f[0], f[1]); w.y = cvt_pk_bf16(f[2], f[3]); w.z = cvt_pk_bf16(f[4], f[5]); w.w = cvt_pk_bf16(f[6], f[7]); return w; }
;     DEV void operator()(const f32x4 (&acc)[2][2][4][2], const Unit& u, int wr, int wc, int fr, int fq) const {
;     ...
; #pragma unroll
;         for (int ai = 0; ai < 2; ++ai)
; #pragma unroll
;             for (int m = 0; m < 4; ++m) {
;                 const int row = row0 + ai * 128 + m * 16;
;                 const float rstd = FUSED ? rstd8[ai * 4 + m] : 1.f;
;                 float h[8];
; #pragma unroll
;                 for (int n = 0; n < 2; ++n)
; #pragma unroll
;                     for (int j = 0; j < 4; ++j) { float g = acc[ai][0][m][n][j], up = acc[ai][1][m][n][j]; if (FUSED) { g = g * rstd + sg[n][j]; up = up * rstd + su[n][j]; } h[4 * n + j] = silu_f(g) * up; }
;                 *(u32x4*)(H + (size_t)row * DFF + col0) = pack8(h);
;             }
	v_fma_f32 v94, v94, v245, v130
	v_fma_f32 v95, v95, v245, v131
	v_fma_f32 v96, v96, v245, v132
	v_fma_f32 v97, v97, v245, v133
	v_fma_f32 v90, v90, v245, v134
	v_fma_f32 v91, v91, v245, v135
	v_fma_f32 v92, v92, v245, v136
	v_fma_f32 v93, v93, v245, v137
	v_mul_f32_e32 v192, 0xbfb8aa3b, v94
	v_mul_f32_e32 v193, 0xbfb8aa3b, v95
	v_mul_f32_e32 v194, 0xbfb8aa3b, v96
	v_mul_f32_e32 v195, 0xbfb8aa3b, v97
	v_mul_f32_e32 v196, 0xbfb8aa3b, v90
	v_mul_f32_e32 v197, 0xbfb8aa3b, v91
	v_mul_f32_e32 v198, 0xbfb8aa3b, v92
	v_mul_f32_e32 v199, 0xbfb8aa3b, v93
	v_exp_f32_e32 v192, v192
	v_exp_f32_e32 v193, v193
	v_exp_f32_e32 v194, v194
	v_exp_f32_e32 v195, v195
	v_exp_f32_e32 v196, v196
	v_exp_f32_e32 v197, v197
	v_exp_f32_e32 v198, v198
	v_exp_f32_e32 v199, v199
	v_fma_f32 v86, v86, v245, v138
	v_fma_f32 v87, v87, v245, v139
	v_fma_f32 v88, v88, v245, v140
	v_fma_f32 v89, v89, v245, v141
	v_fma_f32 v82, v82, v245, v142
	v_fma_f32 v83, v83, v245, v143
	v_fma_f32 v84, v84, v245, v144
	v_fma_f32 v85, v85, v245, v145
	v_add_f32_e32 v192, 1.0, v192
	v_add_f32_e32 v193, 1.0, v193
	v_add_f32_e32 v194, 1.0, v194
	v_add_f32_e32 v195, 1.0, v195
	v_add_f32_e32 v196, 1.0, v196
	v_add_f32_e32 v197, 1.0, v197
	v_add_f32_e32 v198, 1.0, v198
	v_add_f32_e32 v199, 1.0, v199
	v_rcp_f32_e32 v192, v192
	v_rcp_f32_e32 v193, v193
	v_rcp_f32_e32 v194, v194
	v_rcp_f32_e32 v195, v195
	v_rcp_f32_e32 v196, v196
	v_rcp_f32_e32 v197, v197
	v_rcp_f32_e32 v198, v198
	v_rcp_f32_e32 v199, v199
	v_mul_f32_e32 v94, v94, v86
	v_mul_f32_e32 v95, v95, v87
	v_mul_f32_e32 v96, v96, v88
	v_mul_f32_e32 v97, v97, v89
	v_mul_f32_e32 v90, v90, v82
	v_mul_f32_e32 v91, v91, v83
	v_mul_f32_e32 v92, v92, v84
	v_mul_f32_e32 v93, v93, v85
	v_mul_f32_e32 v94, v94, v192
	v_mul_f32_e32 v95, v95, v193
	v_mul_f32_e32 v96, v96, v194
	v_mul_f32_e32 v97, v97, v195
	v_mul_f32_e32 v90, v90, v196
	v_mul_f32_e32 v91, v91, v197
	v_mul_f32_e32 v92, v92, v198
	v_mul_f32_e32 v93, v93, v199
	v_cvt_pk_bf16_f32 v86, v94, v95
	v_cvt_pk_bf16_f32 v87, v96, v97
	v_cvt_pk_bf16_f32 v88, v90, v91
	v_cvt_pk_bf16_f32 v89, v92, v93
	s_add_u32 s98, s56, 0x2c000
	s_addc_u32 s99, s57, 0
	global_store_dwordx4 v204, v[86:89], s[98:99]
	v_fma_f32 v78, v78, v246, v130
	v_fma_f32 v79, v79, v246, v131
	v_fma_f32 v80, v80, v246, v132
	v_fma_f32 v81, v81, v246, v133
	v_fma_f32 v74, v74, v246, v134
	v_fma_f32 v75, v75, v246, v135
	v_fma_f32 v76, v76, v246, v136
	v_fma_f32 v77, v77, v246, v137
	v_mul_f32_e32 v192, 0xbfb8aa3b, v78
	v_mul_f32_e32 v193, 0xbfb8aa3b, v79
	v_mul_f32_e32 v194, 0xbfb8aa3b, v80
	v_mul_f32_e32 v195, 0xbfb8aa3b, v81
	v_mul_f32_e32 v196, 0xbfb8aa3b, v74
	v_mul_f32_e32 v197, 0xbfb8aa3b, v75
	v_mul_f32_e32 v198, 0xbfb8aa3b, v76
	v_mul_f32_e32 v199, 0xbfb8aa3b, v77
	v_exp_f32_e32 v192, v192
	v_exp_f32_e32 v193, v193
	v_exp_f32_e32 v194, v194
	v_exp_f32_e32 v195, v195
	v_exp_f32_e32 v196, v196
	v_exp_f32_e32 v197, v197
	v_exp_f32_e32 v198, v198
	v_exp_f32_e32 v199, v199
	v_fma_f32 v70, v70, v246, v138
	v_fma_f32 v71, v71, v246, v139
	v_fma_f32 v72, v72, v246, v140
	v_fma_f32 v73, v73, v246, v141
	v_fma_f32 v66, v66, v246, v142
	v_fma_f32 v67, v67, v246, v143
	v_fma_f32 v68, v68, v246, v144
	v_fma_f32 v69, v69, v246, v145
	v_add_f32_e32 v192, 1.0, v192
	v_add_f32_e32 v193, 1.0, v193
	v_add_f32_e32 v194, 1.0, v194
	v_add_f32_e32 v195, 1.0, v195
	v_add_f32_e32 v196, 1.0, v196
	v_add_f32_e32 v197, 1.0, v197
	v_add_f32_e32 v198, 1.0, v198
	v_add_f32_e32 v199, 1.0, v199
	v_rcp_f32_e32 v192, v192
	v_rcp_f32_e32 v193, v193
	v_rcp_f32_e32 v194, v194
	v_rcp_f32_e32 v195, v195
	v_rcp_f32_e32 v196, v196
	v_rcp_f32_e32 v197, v197
	v_rcp_f32_e32 v198, v198
	v_rcp_f32_e32 v199, v199
	v_mul_f32_e32 v78, v78, v70
	v_mul_f32_e32 v79, v79, v71
	v_mul_f32_e32 v80, v80, v72
	v_mul_f32_e32 v81, v81, v73
	v_mul_f32_e32 v74, v74, v66
	v_mul_f32_e32 v75, v75, v67
	v_mul_f32_e32 v76, v76, v68
	v_mul_f32_e32 v77, v77, v69
	v_mul_f32_e32 v78, v78, v192
	v_mul_f32_e32 v79, v79, v193
	v_mul_f32_e32 v80, v80, v194
	v_mul_f32_e32 v81, v81, v195
	v_mul_f32_e32 v74, v74, v196
	v_mul_f32_e32 v75, v75, v197
	v_mul_f32_e32 v76, v76, v198
	v_mul_f32_e32 v77, v77, v199
	v_cvt_pk_bf16_f32 v70, v78, v79
	v_cvt_pk_bf16_f32 v71, v80, v81
	v_cvt_pk_bf16_f32 v72, v74, v75
	v_cvt_pk_bf16_f32 v73, v76, v77
	s_add_u32 s98, s56, 0x42000
	s_addc_u32 s99, s57, 0
	global_store_dwordx4 v204, v[70:73], s[98:99]
	v_fma_f32 v62, v62, v247, v130
	v_fma_f32 v63, v63, v247, v131
	v_fma_f32 v64, v64, v247, v132
	v_fma_f32 v65, v65, v247, v133
	v_fma_f32 v58, v58, v247, v134
	v_fma_f32 v59, v59, v247, v135
	v_fma_f32 v60, v60, v247, v136
	v_fma_f32 v61, v61, v247, v137
	v_mul_f32_e32 v192, 0xbfb8aa3b, v62
	v_mul_f32_e32 v193, 0xbfb8aa3b, v63
	v_mul_f32_e32 v194, 0xbfb8aa3b, v64
	v_mul_f32_e32 v195, 0xbfb8aa3b, v65
	v_mul_f32_e32 v196, 0xbfb8aa3b, v58
	v_mul_f32_e32 v197, 0xbfb8aa3b, v59
	v_mul_f32_e32 v198, 0xbfb8aa3b, v60
	v_mul_f32_e32 v199, 0xbfb8aa3b, v61
	v_exp_f32_e32 v192, v192
	v_exp_f32_e32 v193, v193
	v_exp_f32_e32 v194, v194
	v_exp_f32_e32 v195, v195
	v_exp_f32_e32 v196, v196
	v_exp_f32_e32 v197, v197
	v_exp_f32_e32 v198, v198
	v_exp_f32_e32 v199, v199
	v_fma_f32 v54, v54, v247, v138
	v_fma_f32 v55, v55, v247, v139
	v_fma_f32 v56, v56, v247, v140
	v_fma_f32 v57, v57, v247, v141
	v_fma_f32 v50, v50, v247, v142
	v_fma_f32 v51, v51, v247, v143
	v_fma_f32 v52, v52, v247, v144
	v_fma_f32 v53, v53, v247, v145
	v_add_f32_e32 v192, 1.0, v192
	v_add_f32_e32 v193, 1.0, v193
	v_add_f32_e32 v194, 1.0, v194
	v_add_f32_e32 v195, 1.0, v195
	v_add_f32_e32 v196, 1.0, v196
	v_add_f32_e32 v197, 1.0, v197
	v_add_f32_e32 v198, 1.0, v198
	v_add_f32_e32 v199, 1.0, v199
	v_rcp_f32_e32 v192, v192
; DEV float silu_f(float x) { return x * __builtin_amdgcn_rcpf(1.f + __expf(-x)); }
; DEV u32x4 pack8(const float (&f)[8]) { u32x4 w; w.x = cvt_pk_bf16(f[0], f[1]); w.y = cvt_pk_bf16(f[2], f[3]); w.z = cvt_pk_bf16(f[4], f[5]); w.w = cvt_pk_bf16(f[6], f[7]); return w; }
;     DEV void operator()(const f32x4 (&acc)[2][2][4][2], const Unit& u, int wr, int wc, int fr, int fq) const {
;     ...
; #pragma unroll
;         for (int ai = 0; ai < 2; ++ai)
; #pragma unroll
;             for (int m = 0; m < 4; ++m) {
;                 const int row = row0 + ai * 128 + m * 16;
;                 const float rstd = FUSED ? rstd8[ai * 4 + m] : 1.f;
;                 float h[8];
; #pragma unroll
;                 for (int n = 0; n < 2; ++n)
; #pragma unroll
;                     for (int j = 0; j < 4; ++j) { float g = acc[ai][0][m][n][j], up = acc[ai][1][m][n][j]; if (FUSED) { g = g * rstd + sg[n][j]; up = up * rstd + su[n][j]; } h[4 * n + j] = silu_f(g) * up; }
;                 *(u32x4*)(H + (size_t)row * DFF + col0) = pack8(h);
;             }
	v_rcp_f32_e32 v193, v193
	v_rcp_f32_e32 v194, v194
	v_rcp_f32_e32 v195, v195
	v_rcp_f32_e32 v196, v196
	v_rcp_f32_e32 v197, v197
	v_rcp_f32_e32 v198, v198
	v_rcp_f32_e32 v199, v199
	v_mul_f32_e32 v62, v62, v54
	v_mul_f32_e32 v63, v63, v55
	v_mul_f32_e32 v64, v64, v56
	v_mul_f32_e32 v65, v65, v57
	v_mul_f32_e32 v58, v58, v50
	v_mul_f32_e32 v59, v59, v51
	v_mul_f32_e32 v60, v60, v52
	v_mul_f32_e32 v61, v61, v53
	v_mul_f32_e32 v62, v62, v192
	v_mul_f32_e32 v63, v63, v193
	v_mul_f32_e32 v64, v64, v194
	v_mul_f32_e32 v65, v65, v195
	v_mul_f32_e32 v58, v58, v196
	v_mul_f32_e32 v59, v59, v197
	v_mul_f32_e32 v60, v60, v198
	v_mul_f32_e32 v61, v61, v199
	v_cvt_pk_bf16_f32 v54, v62, v63
	v_cvt_pk_bf16_f32 v55, v64, v65
	v_cvt_pk_bf16_f32 v56, v58, v59
	v_cvt_pk_bf16_f32 v57, v60, v61
	s_add_u32 s98, s56, 0xb0000
	s_addc_u32 s99, s57, 0
	global_store_dwordx4 v204, v[54:57], s[98:99]
	v_fma_f32 v46, v46, v248, v130
	v_fma_f32 v47, v47, v248, v131
	v_fma_f32 v48, v48, v248, v132
	v_fma_f32 v49, v49, v248, v133
	v_fma_f32 v42, v42, v248, v134
	v_fma_f32 v43, v43, v248, v135
	v_fma_f32 v44, v44, v248, v136
	v_fma_f32 v45, v45, v248, v137
	v_mul_f32_e32 v192, 0xbfb8aa3b, v46
	v_mul_f32_e32 v193, 0xbfb8aa3b, v47
	v_mul_f32_e32 v194, 0xbfb8aa3b, v48
	v_mul_f32_e32 v195, 0xbfb8aa3b, v49
	v_mul_f32_e32 v196, 0xbfb8aa3b, v42
	v_mul_f32_e32 v197, 0xbfb8aa3b, v43
	v_mul_f32_e32 v198, 0xbfb8aa3b, v44
	v_mul_f32_e32 v199, 0xbfb8aa3b, v45
	v_exp_f32_e32 v192, v192
	v_exp_f32_e32 v193, v193
	v_exp_f32_e32 v194, v194
	v_exp_f32_e32 v195, v195
	v_exp_f32_e32 v196, v196
	v_exp_f32_e32 v197, v197
	v_exp_f32_e32 v198, v198
	v_exp_f32_e32 v199, v199
	v_fma_f32 v38, v38, v248, v138
	v_fma_f32 v39, v39, v248, v139
	v_fma_f32 v40, v40, v248, v140
	v_fma_f32 v41, v41, v248, v141
	v_fma_f32 v34, v34, v248, v142
	v_fma_f32 v35, v35, v248, v143
	v_fma_f32 v36, v36, v248, v144
	v_fma_f32 v37, v37, v248, v145
	v_add_f32_e32 v192, 1.0, v192
	v_add_f32_e32 v193, 1.0, v193
	v_add_f32_e32 v194, 1.0, v194
	v_add_f32_e32 v195, 1.0, v195
	v_add_f32_e32 v196, 1.0, v196
	v_add_f32_e32 v197, 1.0, v197
	v_add_f32_e32 v198, 1.0, v198
	v_add_f32_e32 v199, 1.0, v199
	v_rcp_f32_e32 v192, v192
	v_rcp_f32_e32 v193, v193
	v_rcp_f32_e32 v194, v194
	v_rcp_f32_e32 v195, v195
	v_rcp_f32_e32 v196, v196
	v_rcp_f32_e32 v197, v197
	v_rcp_f32_e32 v198, v198
	v_rcp_f32_e32 v199, v199
	v_mul_f32_e32 v46, v46, v38
	v_mul_f32_e32 v47, v47, v39
	v_mul_f32_e32 v48, v48, v40
	v_mul_f32_e32 v49, v49, v41
	v_mul_f32_e32 v42, v42, v34
	v_mul_f32_e32 v43, v43, v35
	v_mul_f32_e32 v44, v44, v36
	v_mul_f32_e32 v45, v45, v37
	v_mul_f32_e32 v46, v46, v192
	v_mul_f32_e32 v47, v47, v193
	v_mul_f32_e32 v48, v48, v194
	v_mul_f32_e32 v49, v49, v195
	v_mul_f32_e32 v42, v42, v196
	v_mul_f32_e32 v43, v43, v197
	v_mul_f32_e32 v44, v44, v198
	v_mul_f32_e32 v45, v45, v199
	v_cvt_pk_bf16_f32 v38, v46, v47
	v_cvt_pk_bf16_f32 v39, v48, v49
	v_cvt_pk_bf16_f32 v40, v42, v43
	v_cvt_pk_bf16_f32 v41, v44, v45
	s_add_u32 s98, s56, 0xc6000
	s_addc_u32 s99, s57, 0
	global_store_dwordx4 v204, v[38:41], s[98:99]
	v_fma_f32 v30, v30, v249, v130
	v_fma_f32 v31, v31, v249, v131
	v_fma_f32 v32, v32, v249, v132
	v_fma_f32 v33, v33, v249, v133
	v_fma_f32 v26, v26, v249, v134
	v_fma_f32 v27, v27, v249, v135
	v_fma_f32 v28, v28, v249, v136
	v_fma_f32 v29, v29, v249, v137
	v_mul_f32_e32 v192, 0xbfb8aa3b, v30
	v_mul_f32_e32 v193, 0xbfb8aa3b, v31
	v_mul_f32_e32 v194, 0xbfb8aa3b, v32
	v_mul_f32_e32 v195, 0xbfb8aa3b, v33
	v_mul_f32_e32 v196, 0xbfb8aa3b, v26
	v_mul_f32_e32 v197, 0xbfb8aa3b, v27
	v_mul_f32_e32 v198, 0xbfb8aa3b, v28
	v_mul_f32_e32 v199, 0xbfb8aa3b, v29
	v_exp_f32_e32 v192, v192
	v_exp_f32_e32 v193, v193
	v_exp_f32_e32 v194, v194
	v_exp_f32_e32 v195, v195
	v_exp_f32_e32 v196, v196
	v_exp_f32_e32 v197, v197
; DEV float silu_f(float x) { return x * __builtin_amdgcn_rcpf(1.f + __expf(-x)); }
; DEV u32x4 pack8(const float (&f)[8]) { u32x4 w; w.x = cvt_pk_bf16(f[0], f[1]); w.y = cvt_pk_bf16(f[2], f[3]); w.z = cvt_pk_bf16(f[4], f[5]); w.w = cvt_pk_bf16(f[6], f[7]); return w; }
;     DEV void operator()(const f32x4 (&acc)[2][2][4][2], const Unit& u, int wr, int wc, int fr, int fq) const {
;     ...
; #pragma unroll
;         for (int ai = 0; ai < 2; ++ai)
; #pragma unroll
;             for (int m = 0; m < 4; ++m) {
;                 const int row = row0 + ai * 128 + m * 16;
;                 const float rstd = FUSED ? rstd8[ai * 4 + m] : 1.f;
;                 float h[8];
; #pragma unroll
;                 for (int n = 0; n < 2; ++n)
; #pragma unroll
;                     for (int j = 0; j < 4; ++j) { float g = acc[ai][0][m][n][j], up = acc[ai][1][m][n][j]; if (FUSED) { g = g * rstd + sg[n][j]; up = up * rstd + su[n][j]; } h[4 * n + j] = silu_f(g) * up; }
;                 *(u32x4*)(H + (size_t)row * DFF + col0) = pack8(h);
;             }
	v_exp_f32_e32 v198, v198
	v_exp_f32_e32 v199, v199
	v_fma_f32 v22, v22, v249, v138
	v_fma_f32 v23, v23, v249, v139
	v_fma_f32 v24, v24, v249, v140
	v_fma_f32 v25, v25, v249, v141
	v_fma_f32 v18, v18, v249, v142
	v_fma_f32 v19, v19, v249, v143
	v_fma_f32 v20, v20, v249, v144
	v_fma_f32 v21, v21, v249, v145
	v_add_f32_e32 v192, 1.0, v192
	v_add_f32_e32 v193, 1.0, v193
	v_add_f32_e32 v194, 1.0, v194
	v_add_f32_e32 v195, 1.0, v195
	v_add_f32_e32 v196, 1.0, v196
	v_add_f32_e32 v197, 1.0, v197
	v_add_f32_e32 v198, 1.0, v198
	v_add_f32_e32 v199, 1.0, v199
	v_rcp_f32_e32 v192, v192
	v_rcp_f32_e32 v193, v193
	v_rcp_f32_e32 v194, v194
	v_rcp_f32_e32 v195, v195
	v_rcp_f32_e32 v196, v196
	v_rcp_f32_e32 v197, v197
	v_rcp_f32_e32 v198, v198
	v_rcp_f32_e32 v199, v199
	v_mul_f32_e32 v30, v30, v22
	v_mul_f32_e32 v31, v31, v23
	v_mul_f32_e32 v32, v32, v24
	v_mul_f32_e32 v33, v33, v25
	v_mul_f32_e32 v26, v26, v18
	v_mul_f32_e32 v27, v27, v19
	v_mul_f32_e32 v28, v28, v20
	v_mul_f32_e32 v29, v29, v21
	v_mul_f32_e32 v30, v30, v192
	v_mul_f32_e32 v31, v31, v193
	v_mul_f32_e32 v32, v32, v194
	v_mul_f32_e32 v33, v33, v195
	v_mul_f32_e32 v26, v26, v196
	v_mul_f32_e32 v27, v27, v197
	v_mul_f32_e32 v28, v28, v198
	v_mul_f32_e32 v29, v29, v199
	v_cvt_pk_bf16_f32 v22, v30, v31
	v_cvt_pk_bf16_f32 v23, v32, v33
	v_cvt_pk_bf16_f32 v24, v26, v27
	v_cvt_pk_bf16_f32 v25, v28, v29
	s_add_u32 s98, s56, 0xdc000
	s_addc_u32 s99, s57, 0
	global_store_dwordx4 v204, v[22:25], s[98:99]
	v_fma_f32 v14, v14, v250, v130
	v_fma_f32 v15, v15, v250, v131
	v_fma_f32 v16, v16, v250, v132
	v_fma_f32 v17, v17, v250, v133
	v_fma_f32 v10, v10, v250, v134
	v_fma_f32 v11, v11, v250, v135
	v_fma_f32 v12, v12, v250, v136
	v_fma_f32 v13, v13, v250, v137
	v_mul_f32_e32 v192, 0xbfb8aa3b, v14
	v_mul_f32_e32 v193, 0xbfb8aa3b, v15
	v_mul_f32_e32 v194, 0xbfb8aa3b, v16
	v_mul_f32_e32 v195, 0xbfb8aa3b, v17
	v_mul_f32_e32 v196, 0xbfb8aa3b, v10
	v_mul_f32_e32 v197, 0xbfb8aa3b, v11
	v_mul_f32_e32 v198, 0xbfb8aa3b, v12
	v_mul_f32_e32 v199, 0xbfb8aa3b, v13
	v_exp_f32_e32 v192, v192
	v_exp_f32_e32 v193, v193
	v_exp_f32_e32 v194, v194
	v_exp_f32_e32 v195, v195
	v_exp_f32_e32 v196, v196
	v_exp_f32_e32 v197, v197
	v_exp_f32_e32 v198, v198
	v_exp_f32_e32 v199, v199
	v_fma_f32 v6, v6, v250, v138
	v_fma_f32 v7, v7, v250, v139
	v_fma_f32 v8, v8, v250, v140
	v_fma_f32 v9, v9, v250, v141
	v_fma_f32 v2, v2, v250, v142
	v_fma_f32 v3, v3, v250, v143
	v_fma_f32 v4, v4, v250, v144
	v_fma_f32 v5, v5, v250, v145
	v_add_f32_e32 v192, 1.0, v192
	v_add_f32_e32 v193, 1.0, v193
	v_add_f32_e32 v194, 1.0, v194
	v_add_f32_e32 v195, 1.0, v195
	v_add_f32_e32 v196, 1.0, v196
	v_add_f32_e32 v197, 1.0, v197
	v_add_f32_e32 v198, 1.0, v198
	v_add_f32_e32 v199, 1.0, v199
	v_rcp_f32_e32 v192, v192
	v_rcp_f32_e32 v193, v193
	v_rcp_f32_e32 v194, v194
	v_rcp_f32_e32 v195, v195
	v_rcp_f32_e32 v196, v196
	v_rcp_f32_e32 v197, v197
	v_rcp_f32_e32 v198, v198
	v_rcp_f32_e32 v199, v199
	v_mul_f32_e32 v14, v14, v6
	v_mul_f32_e32 v15, v15, v7
	v_mul_f32_e32 v16, v16, v8
	v_mul_f32_e32 v17, v17, v9
	v_mul_f32_e32 v10, v10, v2
	v_mul_f32_e32 v11, v11, v3
	v_mul_f32_e32 v12, v12, v4
	v_mul_f32_e32 v13, v13, v5
	v_mul_f32_e32 v14, v14, v192
	v_mul_f32_e32 v15, v15, v193
	v_mul_f32_e32 v16, v16, v194
	v_mul_f32_e32 v17, v17, v195
	v_mul_f32_e32 v10, v10, v196
	v_mul_f32_e32 v11, v11, v197
	v_mul_f32_e32 v12, v12, v198
	v_mul_f32_e32 v13, v13, v199
	v_cvt_pk_bf16_f32 v6, v14, v15
	v_cvt_pk_bf16_f32 v7, v16, v17
	v_cvt_pk_bf16_f32 v8, v10, v11
	v_cvt_pk_bf16_f32 v9, v12, v13
	s_add_u32 s98, s56, 0xf2000
	s_addc_u32 s99, s57, 0
	global_store_dwordx4 v204, v[6:9], s[98:99]
	s_andn2_b64 vcc, exec, s[4:5]
	s_mov_b64 s[0:1], -1
	s_cbranch_vccnz .LBB0_1891
	s_andn2_b64 vcc, exec, s[10:11]
	s_cbranch_vccnz .LBB0_1890
	s_barrier
	s_branch .LBB0_1890
